# attention tile bodies hand-scheduled: persistent -m block as first-MFMA C operand, lazy max rescale (threshold 4 log2 units), 8-deep LDS fragment prefetch, permlane32 max, 4-chain row sum
# speedup vs baseline: 1.0838x; 1.0389x over previous
.LBB0_1164:
	s_or_b64 exec, exec, s[22:23]
	global_load_dwordx4 v[124:127], v[12:13], off offset:128
	s_movk_i32 s16, 0xd0
	v_mul_lo_u32 v0, v17, s16
	v_add_u32_e32 v1, 32, v0
	v_lshrrev_b32_e32 v2, 2, v144
	v_add_u32_e32 v134, v1, v10
	s_movk_i32 s51, 0xd0
	v_mul_lo_u32 v0, v2, s16
	v_and_b32_e32 v135, 48, v18
	ds_write_b128 v134, v[80:83]
	s_and_saveexec_b64 s[22:23], s[0:1]
	s_xor_b64 s[0:1], exec, s[22:23]
	v_mul_lo_u32 v0, v2, s51
	v_and_b32_e32 v135, 48, v18
	s_andn2_saveexec_b64 s[0:1], s[0:1]
	v_add3_u32 v2, 32, v0, v135
	ds_write_b128 v2, v[84:87] offset:128
	s_or_b64 exec, exec, s[0:1]
	v_lshlrev_b32_e32 v3, 3, v144
	v_lshlrev_b32_e32 v5, 6, v17
	v_and_b32_e32 v3, 8, v3
	s_movk_i32 s0, 0x60
	v_sub_u32_e32 v1, v1, v5
	v_and_or_b32 v3, v18, s0, v3
	v_cmp_lt_i32_e32 vcc, v248, v242
	v_and_b32_e32 v2, 31, v144
	v_add_u32_e32 v136, v1, v3
	v_cndmask_b32_e32 v1, v241, v248, vcc
	v_mad_u32_u24 v18, v2, s51, 32
	v_lshlrev_b32_e32 v146, 2, v1
	v_lshlrev_b32_e32 v1, 6, v2
	v_add_u32_e32 v147, 32, v0
	v_and_b32_e32 v0, 7, v144
	v_sub_u32_e32 v19, v18, v1
	v_lshlrev_b32_e32 v0, 4, v0
	v_mov_b32_e32 v1, v4
	v_lshlrev_b32_e32 v2, 1, v17
	v_mad_i64_i32 v[0:1], s[0:1], v2, s35, v[0:1]
	v_lshl_add_u64 v[0:1], s[20:21], 0, v[0:1]
	v_mov_b32_e32 v14, v4
	v_mov_b32_e32 v15, v4
	v_lshlrev_b64 v[128:129], 4, v[144:145]
	v_lshl_add_u64 v[130:131], v[0:1], 0, s[96:97]
	v_mov_b32_e32 v0, v4
	v_mov_b32_e32 v1, v4
	v_mov_b32_e32 v2, v4
	v_mov_b32_e32 v3, v4
	v_mov_b32_e32 v5, v4
	v_mov_b32_e32 v6, v4
	v_mov_b32_e32 v7, v4
	v_mov_b32_e32 v8, v4
	v_mov_b32_e32 v9, v4
	v_mov_b32_e32 v10, v4
	v_mov_b32_e32 v11, v4
	v_mov_b32_e32 v12, v4
	v_mov_b32_e32 v13, v4
	v_add_u32_e32 v144, v18, v16
	v_add_u32_e32 v145, v19, v16
	v_mov_b64_e32 v[30:31], v[14:15]
	v_mov_b64_e32 v[46:47], v[14:15]
	s_lshr_b32 s16, s35, 6
	v_add_u32_e32 v137, 0x3000, v136
	v_mov_b32_e32 v182, 0x80000000
	v_mov_b32_e32 v183, v182
	v_mov_b32_e32 v184, v182
	v_mov_b32_e32 v185, v182
	v_mov_b32_e32 v186, v182
	v_mov_b32_e32 v187, v182
	v_mov_b32_e32 v188, v182
	v_mov_b32_e32 v189, v182
	v_mov_b32_e32 v190, v182
	v_mov_b32_e32 v191, v182
	v_mov_b32_e32 v192, v182
	v_mov_b32_e32 v193, v182
	v_mov_b32_e32 v194, v182
	v_mov_b32_e32 v195, v182
	v_mov_b32_e32 v196, v182
	v_mov_b32_e32 v197, v182
	v_mov_b32_e32 v148, 0
	s_mov_b32 s22, 3
	v_mov_b64_e32 v[28:29], v[12:13]
	v_mov_b64_e32 v[26:27], v[10:11]
	v_mov_b64_e32 v[24:25], v[8:9]
	v_mov_b64_e32 v[22:23], v[6:7]
	v_mov_b64_e32 v[20:21], v[4:5]
	v_mov_b64_e32 v[18:19], v[2:3]
	v_mov_b64_e32 v[16:17], v[0:1]
	v_mov_b64_e32 v[44:45], v[12:13]
	v_mov_b64_e32 v[42:43], v[10:11]
	v_mov_b64_e32 v[40:41], v[8:9]
	v_mov_b64_e32 v[38:39], v[6:7]
	v_mov_b64_e32 v[36:37], v[4:5]
	v_mov_b64_e32 v[34:35], v[2:3]
	v_mov_b64_e32 v[32:33], v[0:1]
	v_mov_b32_e32 v0, 0
	s_waitcnt vmcnt(1)
	ds_write2_b64 v137, v[120:121], v[122:123] offset0:128 offset1:130
	s_waitcnt lgkmcnt(0)
	s_barrier
	s_branch .LBB0_1171

.LBB0_1170:
	s_add_u32 s14, s14, 0x2000
	s_addc_u32 s15, s15, 0
	s_add_u32 s12, s12, 0x4000
	s_addc_u32 s13, s13, 0
	s_add_i32 s22, s22, 2
	s_cmp_lt_u32 s23, s16
	v_lshl_add_u64 v[130:131], v[130:131], 0, s[96:97]
	s_waitcnt lgkmcnt(0)
	s_barrier
	s_cbranch_scc0 .LBB0_1053

.LBB0_1175:
	ds_read_b128 v[150:153], v144
	ds_read_b128 v[154:157], v144 offset:32
	ds_read_b128 v[158:161], v144 offset:64
	ds_read_b128 v[162:165], v144 offset:96
	ds_read_b128 v[166:169], v144 offset:128
	ds_read_b128 v[170:173], v144 offset:160
	ds_read_b128 v[174:177], v144 offset:6656
	ds_read_b128 v[178:181], v144 offset:6688
	s_waitcnt lgkmcnt(7)
	v_mfma_f32_32x32x16_bf16 v[64:79], v[150:153], v[96:99], v[182:197]
	ds_read_b128 v[150:153], v144 offset:6720
	s_waitcnt lgkmcnt(7)
	v_mfma_f32_32x32x16_bf16 v[64:79], v[154:157], v[100:103], v[64:79]
	ds_read_b128 v[154:157], v144 offset:6752
	s_waitcnt lgkmcnt(7)
	v_mfma_f32_32x32x16_bf16 v[64:79], v[158:161], v[104:107], v[64:79]
	ds_read_b128 v[158:161], v144 offset:6784
	s_waitcnt lgkmcnt(7)
	v_mfma_f32_32x32x16_bf16 v[64:79], v[162:165], v[108:111], v[64:79]
	ds_read_b128 v[162:165], v144 offset:6816
	s_waitcnt lgkmcnt(7)
	v_mfma_f32_32x32x16_bf16 v[64:79], v[166:169], v[112:115], v[64:79]
	ds_read_b128 v[166:169], v145 offset:13312
	s_waitcnt lgkmcnt(7)
	v_mfma_f32_32x32x16_bf16 v[64:79], v[170:173], v[116:119], v[64:79]
	ds_read_b128 v[170:173], v145 offset:17920
	s_waitcnt lgkmcnt(7)
	v_mfma_f32_32x32x16_bf16 v[48:63], v[174:177], v[96:99], v[182:197]
	ds_read_b128 v[174:177], v145 offset:17952
	s_waitcnt lgkmcnt(7)
	v_mfma_f32_32x32x16_bf16 v[48:63], v[178:181], v[100:103], v[48:63]
	ds_read_b128 v[178:181], v145 offset:13344
	s_waitcnt lgkmcnt(7)
	v_mfma_f32_32x32x16_bf16 v[48:63], v[150:153], v[104:107], v[48:63]
	ds_read_b128 v[150:153], v145 offset:13376
	s_waitcnt lgkmcnt(7)
	v_mfma_f32_32x32x16_bf16 v[48:63], v[154:157], v[108:111], v[48:63]
	ds_read_b128 v[154:157], v145 offset:17984
	v_max3_f32 v214, v64, v65, v66
	v_max3_f32 v214, v214, v67, v68
	v_max3_f32 v214, v214, v69, v70
	v_max3_f32 v214, v214, v71, v72
	s_waitcnt lgkmcnt(7)
	v_mfma_f32_32x32x16_bf16 v[48:63], v[158:161], v[112:115], v[48:63]
	ds_read_b128 v[158:161], v145 offset:13408
	v_max3_f32 v214, v214, v73, v74
	v_max3_f32 v214, v214, v75, v76
	v_max3_f32 v214, v214, v77, v78
	v_max_f32_e32 v214, v214, v79
	s_waitcnt lgkmcnt(7)
	v_mfma_f32_32x32x16_bf16 v[48:63], v[162:165], v[116:119], v[48:63]
	ds_read_b128 v[162:165], v145 offset:18016
	s_nop 10
	v_max3_f32 v214, v214, v48, v49
	v_max3_f32 v214, v214, v50, v51
	v_max3_f32 v214, v214, v52, v53
	v_max3_f32 v214, v214, v54, v55
	v_max3_f32 v214, v214, v56, v57
	v_max3_f32 v214, v214, v58, v59
	v_max3_f32 v214, v214, v60, v61
	v_max3_f32 v214, v214, v62, v63
	v_mov_b32_e32 v215, v214
	v_mov_b32_e32 v216, v214
	s_nop 1
	v_permlane32_swap_b32_e32 v215, v216
	v_max3_f32 v214, v214, v215, v216
	v_cmp_lt_f32_e32 vcc, 4.0, v214
	s_cbranch_vccz .Lattn_fast_a
	v_max_f32_e32 v222, 0, v214
	v_exp_f32_e64 v224, -v222
	v_add_f32_e32 v0, v0, v222
	v_xor_b32_e32 v182, 0x80000000, v0
	v_mov_b32_e32 v183, v182
	v_mov_b32_e32 v184, v182
	v_mov_b32_e32 v185, v182
	v_mov_b32_e32 v186, v182
	v_mov_b32_e32 v187, v182
	v_mov_b32_e32 v188, v182
	v_mov_b32_e32 v189, v182
	v_mov_b32_e32 v190, v182
	v_mov_b32_e32 v191, v182
	v_mov_b32_e32 v192, v182
	v_mov_b32_e32 v193, v182
	v_mov_b32_e32 v194, v182
	v_mov_b32_e32 v195, v182
	v_mov_b32_e32 v196, v182
	v_mov_b32_e32 v197, v182
	v_pk_add_f32 v[64:65], v[64:65], v[222:223] op_sel_hi:[1,0] neg_lo:[0,1] neg_hi:[0,1]
	v_pk_add_f32 v[48:49], v[48:49], v[222:223] op_sel_hi:[1,0] neg_lo:[0,1] neg_hi:[0,1]
	v_pk_add_f32 v[66:67], v[66:67], v[222:223] op_sel_hi:[1,0] neg_lo:[0,1] neg_hi:[0,1]
	v_pk_add_f32 v[50:51], v[50:51], v[222:223] op_sel_hi:[1,0] neg_lo:[0,1] neg_hi:[0,1]
	v_pk_add_f32 v[68:69], v[68:69], v[222:223] op_sel_hi:[1,0] neg_lo:[0,1] neg_hi:[0,1]
	v_pk_add_f32 v[52:53], v[52:53], v[222:223] op_sel_hi:[1,0] neg_lo:[0,1] neg_hi:[0,1]
	v_pk_add_f32 v[70:71], v[70:71], v[222:223] op_sel_hi:[1,0] neg_lo:[0,1] neg_hi:[0,1]
	v_pk_add_f32 v[54:55], v[54:55], v[222:223] op_sel_hi:[1,0] neg_lo:[0,1] neg_hi:[0,1]
	v_pk_add_f32 v[72:73], v[72:73], v[222:223] op_sel_hi:[1,0] neg_lo:[0,1] neg_hi:[0,1]
	v_pk_add_f32 v[56:57], v[56:57], v[222:223] op_sel_hi:[1,0] neg_lo:[0,1] neg_hi:[0,1]
	v_pk_add_f32 v[74:75], v[74:75], v[222:223] op_sel_hi:[1,0] neg_lo:[0,1] neg_hi:[0,1]
	v_pk_add_f32 v[58:59], v[58:59], v[222:223] op_sel_hi:[1,0] neg_lo:[0,1] neg_hi:[0,1]
	v_pk_add_f32 v[76:77], v[76:77], v[222:223] op_sel_hi:[1,0] neg_lo:[0,1] neg_hi:[0,1]
	v_pk_add_f32 v[60:61], v[60:61], v[222:223] op_sel_hi:[1,0] neg_lo:[0,1] neg_hi:[0,1]
	v_pk_add_f32 v[78:79], v[78:79], v[222:223] op_sel_hi:[1,0] neg_lo:[0,1] neg_hi:[0,1]
	v_pk_add_f32 v[62:63], v[62:63], v[222:223] op_sel_hi:[1,0] neg_lo:[0,1] neg_hi:[0,1]
	v_mul_f32_e32 v148, v148, v224
	v_pk_mul_f32 v[46:47], v[46:47], v[224:225] op_sel_hi:[1,0]
	v_pk_mul_f32 v[44:45], v[44:45], v[224:225] op_sel_hi:[1,0]
	v_pk_mul_f32 v[42:43], v[42:43], v[224:225] op_sel_hi:[1,0]
	v_pk_mul_f32 v[40:41], v[40:41], v[224:225] op_sel_hi:[1,0]
	v_pk_mul_f32 v[38:39], v[38:39], v[224:225] op_sel_hi:[1,0]
	v_pk_mul_f32 v[36:37], v[36:37], v[224:225] op_sel_hi:[1,0]
	v_pk_mul_f32 v[34:35], v[34:35], v[224:225] op_sel_hi:[1,0]
	v_pk_mul_f32 v[32:33], v[32:33], v[224:225] op_sel_hi:[1,0]
	v_pk_mul_f32 v[30:31], v[30:31], v[224:225] op_sel_hi:[1,0]
	v_pk_mul_f32 v[28:29], v[28:29], v[224:225] op_sel_hi:[1,0]
	v_pk_mul_f32 v[26:27], v[26:27], v[224:225] op_sel_hi:[1,0]
	v_pk_mul_f32 v[24:25], v[24:25], v[224:225] op_sel_hi:[1,0]
	v_pk_mul_f32 v[22:23], v[22:23], v[224:225] op_sel_hi:[1,0]
	v_pk_mul_f32 v[20:21], v[20:21], v[224:225] op_sel_hi:[1,0]
	v_pk_mul_f32 v[18:19], v[18:19], v[224:225] op_sel_hi:[1,0]
	v_pk_mul_f32 v[16:17], v[16:17], v[224:225] op_sel_hi:[1,0]
.Lattn_fast_a:
	v_exp_f32_e32 v64, v64
	v_exp_f32_e32 v65, v65
	v_exp_f32_e32 v66, v66
	v_exp_f32_e32 v67, v67
	v_exp_f32_e32 v68, v68
	v_exp_f32_e32 v69, v69
	v_exp_f32_e32 v70, v70
	v_exp_f32_e32 v71, v71
	v_cvt_pk_bf16_f32 v230, v64, v65
	v_cvt_pk_bf16_f32 v231, v66, v67
	v_cvt_pk_bf16_f32 v232, v68, v69
	v_cvt_pk_bf16_f32 v233, v70, v71
	v_exp_f32_e32 v72, v72
	s_waitcnt lgkmcnt(7)
	v_mfma_f32_32x32x16_bf16 v[32:47], v[166:169], v[230:233], v[32:47]
	v_exp_f32_e32 v73, v73
	v_exp_f32_e32 v74, v74
	v_exp_f32_e32 v75, v75
	v_add_f32_e32 v218, v64, v65
	v_add_f32_e32 v219, v66, v67
	s_waitcnt lgkmcnt(6)
	v_mfma_f32_32x32x16_bf16 v[16:31], v[170:173], v[230:233], v[16:31]
	v_exp_f32_e32 v76, v76
	v_exp_f32_e32 v77, v77
	v_exp_f32_e32 v78, v78
	v_exp_f32_e32 v79, v79
	v_add_f32_e32 v220, v68, v69
	v_add_f32_e32 v221, v70, v71
	v_cvt_pk_bf16_f32 v234, v72, v73
	v_cvt_pk_bf16_f32 v235, v74, v75
	v_cvt_pk_bf16_f32 v236, v76, v77
	v_cvt_pk_bf16_f32 v237, v78, v79
	v_add_f32_e32 v218, v218, v72
	s_waitcnt lgkmcnt(5)
	v_mfma_f32_32x32x16_bf16 v[16:31], v[174:177], v[234:237], v[16:31]
	v_add_f32_e32 v218, v218, v73
	v_add_f32_e32 v219, v219, v74
	v_add_f32_e32 v219, v219, v75
	v_exp_f32_e32 v48, v48
	v_exp_f32_e32 v49, v49
	s_waitcnt lgkmcnt(4)
	v_mfma_f32_32x32x16_bf16 v[32:47], v[178:181], v[234:237], v[32:47]
	v_exp_f32_e32 v50, v50
	v_exp_f32_e32 v51, v51
	v_exp_f32_e32 v52, v52
	v_exp_f32_e32 v53, v53
	v_add_f32_e32 v220, v220, v76
	v_add_f32_e32 v220, v220, v77
	v_exp_f32_e32 v54, v54
	v_exp_f32_e32 v55, v55
	v_add_f32_e32 v221, v221, v78
	v_add_f32_e32 v221, v221, v79
	v_cvt_pk_bf16_f32 v230, v48, v49
	v_cvt_pk_bf16_f32 v231, v50, v51
	v_cvt_pk_bf16_f32 v232, v52, v53
	v_cvt_pk_bf16_f32 v233, v54, v55
	v_add_f32_e32 v218, v218, v48
	s_waitcnt lgkmcnt(3)
	v_mfma_f32_32x32x16_bf16 v[32:47], v[150:153], v[230:233], v[32:47]
	v_exp_f32_e32 v56, v56
	v_exp_f32_e32 v57, v57
	v_exp_f32_e32 v58, v58
	v_add_f32_e32 v218, v218, v49
	v_add_f32_e32 v219, v219, v50
	s_waitcnt lgkmcnt(2)
	v_mfma_f32_32x32x16_bf16 v[16:31], v[154:157], v[230:233], v[16:31]
	v_exp_f32_e32 v59, v59
	v_exp_f32_e32 v60, v60
	v_exp_f32_e32 v61, v61
	v_exp_f32_e32 v62, v62
	v_exp_f32_e32 v63, v63
	v_add_f32_e32 v219, v219, v51
	v_add_f32_e32 v220, v220, v52
	v_add_f32_e32 v220, v220, v53
	v_add_f32_e32 v221, v221, v54
	v_add_f32_e32 v221, v221, v55
	v_cvt_pk_bf16_f32 v234, v56, v57
	v_cvt_pk_bf16_f32 v235, v58, v59
	v_cvt_pk_bf16_f32 v236, v60, v61
	v_cvt_pk_bf16_f32 v237, v62, v63
	v_add_f32_e32 v218, v218, v56
	s_waitcnt lgkmcnt(1)
	v_mfma_f32_32x32x16_bf16 v[32:47], v[158:161], v[234:237], v[32:47]
	v_add_f32_e32 v218, v218, v57
	v_add_f32_e32 v219, v219, v58
	v_add_f32_e32 v219, v219, v59
	v_add_f32_e32 v220, v220, v60
	s_waitcnt lgkmcnt(0)
	v_mfma_f32_32x32x16_bf16 v[16:31], v[162:165], v[234:237], v[16:31]
	v_add_f32_e32 v220, v220, v61
	v_add_f32_e32 v221, v221, v62
	v_add_f32_e32 v221, v221, v63
	v_add_f32_e32 v218, v218, v219
	v_add_f32_e32 v220, v220, v221
	v_add_f32_e32 v218, v218, v220
	v_add_f32_e32 v148, v148, v218
	s_waitcnt vmcnt(1)
	ds_write_b128 v134, v[88:91] offset:22528
	s_and_saveexec_b64 s[20:21], s[4:5]
	v_add_u32_e32 v66, v147, v135
	ds_write_b128 v66, v[92:95] offset:22656
	s_or_b64 exec, exec, s[20:21]
	v_add_u32_e32 v66, 0x8800, v136
	s_cmp_ge_u32 s22, s16
	s_waitcnt vmcnt(0)
	ds_write2_b64 v66, v[124:125], v[126:127] offset0:128 offset1:130
	s_waitcnt lgkmcnt(0)
	s_barrier
	s_cbranch_scc1 .LBB0_1183
	v_lshl_add_u64 v[66:67], s[12:13], 0, v[128:129]
	v_add_co_u32_e32 v66, vcc, 0x6000, v66
	s_nop 1
	v_addc_co_u32_e32 v67, vcc, 0, v67, vcc
	global_load_dwordx4 v[88:91], v[66:67], off
	s_and_saveexec_b64 s[20:21], s[4:5]
	s_cbranch_execz .LBB0_1182
	v_lshl_add_u64 v[66:67], s[14:15], 0, v[128:129]
	v_add_co_u32_e32 v66, vcc, 0x3000, v66
	s_nop 1
	v_addc_co_u32_e32 v67, vcc, 0, v67, vcc
	global_load_dwordx4 v[92:95], v[66:67], off

.LBB0_1183:
	ds_read_b128 v[150:153], v144 offset:22528
	ds_read_b128 v[154:157], v144 offset:22560
	ds_read_b128 v[158:161], v144 offset:22592
	ds_read_b128 v[162:165], v144 offset:22624
	ds_read_b128 v[166:169], v144 offset:22656
	ds_read_b128 v[170:173], v144 offset:22688
	ds_read_b128 v[174:177], v144 offset:29184
	ds_read_b128 v[178:181], v144 offset:29216
	s_waitcnt lgkmcnt(7)
	v_mfma_f32_32x32x16_bf16 v[64:79], v[150:153], v[96:99], v[182:197]
	ds_read_b128 v[150:153], v144 offset:29248
	s_waitcnt lgkmcnt(7)
	v_mfma_f32_32x32x16_bf16 v[64:79], v[154:157], v[100:103], v[64:79]
	ds_read_b128 v[154:157], v144 offset:29280
	s_waitcnt lgkmcnt(7)
	v_mfma_f32_32x32x16_bf16 v[64:79], v[158:161], v[104:107], v[64:79]
	ds_read_b128 v[158:161], v144 offset:29312
	s_waitcnt lgkmcnt(7)
	v_mfma_f32_32x32x16_bf16 v[64:79], v[162:165], v[108:111], v[64:79]
	ds_read_b128 v[162:165], v144 offset:29344
	s_waitcnt lgkmcnt(7)
	v_mfma_f32_32x32x16_bf16 v[64:79], v[166:169], v[112:115], v[64:79]
	ds_read_b128 v[166:169], v145 offset:35840
	s_waitcnt lgkmcnt(7)
	v_mfma_f32_32x32x16_bf16 v[64:79], v[170:173], v[116:119], v[64:79]
	ds_read_b128 v[170:173], v145 offset:40448
	s_waitcnt lgkmcnt(7)
	v_mfma_f32_32x32x16_bf16 v[48:63], v[174:177], v[96:99], v[182:197]
	ds_read_b128 v[174:177], v145 offset:40480
	s_waitcnt lgkmcnt(7)
	v_mfma_f32_32x32x16_bf16 v[48:63], v[178:181], v[100:103], v[48:63]
	ds_read_b128 v[178:181], v145 offset:35872
	s_waitcnt lgkmcnt(7)
	v_mfma_f32_32x32x16_bf16 v[48:63], v[150:153], v[104:107], v[48:63]
	ds_read_b128 v[150:153], v145 offset:35904
	s_waitcnt lgkmcnt(7)
	v_mfma_f32_32x32x16_bf16 v[48:63], v[154:157], v[108:111], v[48:63]
	ds_read_b128 v[154:157], v145 offset:40512
	v_max3_f32 v214, v64, v65, v66
	v_max3_f32 v214, v214, v67, v68
	v_max3_f32 v214, v214, v69, v70
	v_max3_f32 v214, v214, v71, v72
	s_waitcnt lgkmcnt(7)
	v_mfma_f32_32x32x16_bf16 v[48:63], v[158:161], v[112:115], v[48:63]
	ds_read_b128 v[158:161], v145 offset:35936
	v_max3_f32 v214, v214, v73, v74
	v_max3_f32 v214, v214, v75, v76
	v_max3_f32 v214, v214, v77, v78
	v_max_f32_e32 v214, v214, v79
	s_waitcnt lgkmcnt(7)
	v_mfma_f32_32x32x16_bf16 v[48:63], v[162:165], v[116:119], v[48:63]
	ds_read_b128 v[162:165], v145 offset:40544
	s_nop 10
	v_max3_f32 v214, v214, v48, v49
	v_max3_f32 v214, v214, v50, v51
	v_max3_f32 v214, v214, v52, v53
	v_max3_f32 v214, v214, v54, v55
	v_max3_f32 v214, v214, v56, v57
	v_max3_f32 v214, v214, v58, v59
	v_max3_f32 v214, v214, v60, v61
	v_max3_f32 v214, v214, v62, v63
	v_mov_b32_e32 v215, v214
	v_mov_b32_e32 v216, v214
	s_nop 1
	v_permlane32_swap_b32_e32 v215, v216
	v_max3_f32 v214, v214, v215, v216
	v_cmp_lt_f32_e32 vcc, 4.0, v214
	s_cbranch_vccz .Lattn_fast_b
	v_max_f32_e32 v222, 0, v214
	v_exp_f32_e64 v224, -v222
	v_add_f32_e32 v0, v0, v222
	v_xor_b32_e32 v182, 0x80000000, v0
	v_mov_b32_e32 v183, v182
	v_mov_b32_e32 v184, v182
	v_mov_b32_e32 v185, v182
	v_mov_b32_e32 v186, v182
	v_mov_b32_e32 v187, v182
	v_mov_b32_e32 v188, v182
	v_mov_b32_e32 v189, v182
	v_mov_b32_e32 v190, v182
	v_mov_b32_e32 v191, v182
	v_mov_b32_e32 v192, v182
	v_mov_b32_e32 v193, v182
	v_mov_b32_e32 v194, v182
	v_mov_b32_e32 v195, v182
	v_mov_b32_e32 v196, v182
	v_mov_b32_e32 v197, v182
	v_pk_add_f32 v[64:65], v[64:65], v[222:223] op_sel_hi:[1,0] neg_lo:[0,1] neg_hi:[0,1]
	v_pk_add_f32 v[48:49], v[48:49], v[222:223] op_sel_hi:[1,0] neg_lo:[0,1] neg_hi:[0,1]
	v_pk_add_f32 v[66:67], v[66:67], v[222:223] op_sel_hi:[1,0] neg_lo:[0,1] neg_hi:[0,1]
	v_pk_add_f32 v[50:51], v[50:51], v[222:223] op_sel_hi:[1,0] neg_lo:[0,1] neg_hi:[0,1]
	v_pk_add_f32 v[68:69], v[68:69], v[222:223] op_sel_hi:[1,0] neg_lo:[0,1] neg_hi:[0,1]
	v_pk_add_f32 v[52:53], v[52:53], v[222:223] op_sel_hi:[1,0] neg_lo:[0,1] neg_hi:[0,1]
	v_pk_add_f32 v[70:71], v[70:71], v[222:223] op_sel_hi:[1,0] neg_lo:[0,1] neg_hi:[0,1]
	v_pk_add_f32 v[54:55], v[54:55], v[222:223] op_sel_hi:[1,0] neg_lo:[0,1] neg_hi:[0,1]
	v_pk_add_f32 v[72:73], v[72:73], v[222:223] op_sel_hi:[1,0] neg_lo:[0,1] neg_hi:[0,1]
	v_pk_add_f32 v[56:57], v[56:57], v[222:223] op_sel_hi:[1,0] neg_lo:[0,1] neg_hi:[0,1]
	v_pk_add_f32 v[74:75], v[74:75], v[222:223] op_sel_hi:[1,0] neg_lo:[0,1] neg_hi:[0,1]
	v_pk_add_f32 v[58:59], v[58:59], v[222:223] op_sel_hi:[1,0] neg_lo:[0,1] neg_hi:[0,1]
	v_pk_add_f32 v[76:77], v[76:77], v[222:223] op_sel_hi:[1,0] neg_lo:[0,1] neg_hi:[0,1]
	v_pk_add_f32 v[60:61], v[60:61], v[222:223] op_sel_hi:[1,0] neg_lo:[0,1] neg_hi:[0,1]
	v_pk_add_f32 v[78:79], v[78:79], v[222:223] op_sel_hi:[1,0] neg_lo:[0,1] neg_hi:[0,1]
	v_pk_add_f32 v[62:63], v[62:63], v[222:223] op_sel_hi:[1,0] neg_lo:[0,1] neg_hi:[0,1]
	v_mul_f32_e32 v148, v148, v224
	v_pk_mul_f32 v[46:47], v[46:47], v[224:225] op_sel_hi:[1,0]
	v_pk_mul_f32 v[44:45], v[44:45], v[224:225] op_sel_hi:[1,0]
	v_pk_mul_f32 v[42:43], v[42:43], v[224:225] op_sel_hi:[1,0]
	v_pk_mul_f32 v[40:41], v[40:41], v[224:225] op_sel_hi:[1,0]
	v_pk_mul_f32 v[38:39], v[38:39], v[224:225] op_sel_hi:[1,0]
	v_pk_mul_f32 v[36:37], v[36:37], v[224:225] op_sel_hi:[1,0]
	v_pk_mul_f32 v[34:35], v[34:35], v[224:225] op_sel_hi:[1,0]
	v_pk_mul_f32 v[32:33], v[32:33], v[224:225] op_sel_hi:[1,0]
	v_pk_mul_f32 v[30:31], v[30:31], v[224:225] op_sel_hi:[1,0]
	v_pk_mul_f32 v[28:29], v[28:29], v[224:225] op_sel_hi:[1,0]
	v_pk_mul_f32 v[26:27], v[26:27], v[224:225] op_sel_hi:[1,0]
	v_pk_mul_f32 v[24:25], v[24:25], v[224:225] op_sel_hi:[1,0]
	v_pk_mul_f32 v[22:23], v[22:23], v[224:225] op_sel_hi:[1,0]
	v_pk_mul_f32 v[20:21], v[20:21], v[224:225] op_sel_hi:[1,0]
	v_pk_mul_f32 v[18:19], v[18:19], v[224:225] op_sel_hi:[1,0]
	v_pk_mul_f32 v[16:17], v[16:17], v[224:225] op_sel_hi:[1,0]
.Lattn_fast_b:
	v_exp_f32_e32 v64, v64
	v_exp_f32_e32 v65, v65
	v_exp_f32_e32 v66, v66
	v_exp_f32_e32 v67, v67
	v_exp_f32_e32 v68, v68
	v_exp_f32_e32 v69, v69
	v_exp_f32_e32 v70, v70
	v_exp_f32_e32 v71, v71
	v_cvt_pk_bf16_f32 v230, v64, v65
	v_cvt_pk_bf16_f32 v231, v66, v67
	v_cvt_pk_bf16_f32 v232, v68, v69
	v_cvt_pk_bf16_f32 v233, v70, v71
	v_exp_f32_e32 v72, v72
	s_waitcnt lgkmcnt(7)
	v_mfma_f32_32x32x16_bf16 v[32:47], v[166:169], v[230:233], v[32:47]
	v_exp_f32_e32 v73, v73
	v_exp_f32_e32 v74, v74
	v_exp_f32_e32 v75, v75
	v_add_f32_e32 v218, v64, v65
	v_add_f32_e32 v219, v66, v67
	s_waitcnt lgkmcnt(6)
	v_mfma_f32_32x32x16_bf16 v[16:31], v[170:173], v[230:233], v[16:31]
	v_exp_f32_e32 v76, v76
	v_exp_f32_e32 v77, v77
	v_exp_f32_e32 v78, v78
	v_exp_f32_e32 v79, v79
	v_add_f32_e32 v220, v68, v69
	v_add_f32_e32 v221, v70, v71
	v_cvt_pk_bf16_f32 v234, v72, v73
	v_cvt_pk_bf16_f32 v235, v74, v75
	v_cvt_pk_bf16_f32 v236, v76, v77
	v_cvt_pk_bf16_f32 v237, v78, v79
	v_add_f32_e32 v218, v218, v72
	s_waitcnt lgkmcnt(5)
	v_mfma_f32_32x32x16_bf16 v[16:31], v[174:177], v[234:237], v[16:31]
	v_add_f32_e32 v218, v218, v73
	v_add_f32_e32 v219, v219, v74
	v_add_f32_e32 v219, v219, v75
	v_exp_f32_e32 v48, v48
	v_exp_f32_e32 v49, v49
	s_waitcnt lgkmcnt(4)
	v_mfma_f32_32x32x16_bf16 v[32:47], v[178:181], v[234:237], v[32:47]
	v_exp_f32_e32 v50, v50
	v_exp_f32_e32 v51, v51
	v_exp_f32_e32 v52, v52
	v_exp_f32_e32 v53, v53
	v_add_f32_e32 v220, v220, v76
	v_add_f32_e32 v220, v220, v77
	v_exp_f32_e32 v54, v54
	v_exp_f32_e32 v55, v55
	v_add_f32_e32 v221, v221, v78
	v_add_f32_e32 v221, v221, v79
	v_cvt_pk_bf16_f32 v230, v48, v49
	v_cvt_pk_bf16_f32 v231, v50, v51
	v_cvt_pk_bf16_f32 v232, v52, v53
	v_cvt_pk_bf16_f32 v233, v54, v55
	v_add_f32_e32 v218, v218, v48
	s_waitcnt lgkmcnt(3)
	v_mfma_f32_32x32x16_bf16 v[32:47], v[150:153], v[230:233], v[32:47]
	v_exp_f32_e32 v56, v56
	v_exp_f32_e32 v57, v57
	v_exp_f32_e32 v58, v58
	v_add_f32_e32 v218, v218, v49
	v_add_f32_e32 v219, v219, v50
	s_waitcnt lgkmcnt(2)
	v_mfma_f32_32x32x16_bf16 v[16:31], v[154:157], v[230:233], v[16:31]
	v_exp_f32_e32 v59, v59
	v_exp_f32_e32 v60, v60
	v_exp_f32_e32 v61, v61
	v_exp_f32_e32 v62, v62
	v_exp_f32_e32 v63, v63
	v_add_f32_e32 v219, v219, v51
	v_add_f32_e32 v220, v220, v52
	v_add_f32_e32 v220, v220, v53
	v_add_f32_e32 v221, v221, v54
	v_add_f32_e32 v221, v221, v55
	v_cvt_pk_bf16_f32 v234, v56, v57
	v_cvt_pk_bf16_f32 v235, v58, v59
	v_cvt_pk_bf16_f32 v236, v60, v61
	v_cvt_pk_bf16_f32 v237, v62, v63
	v_add_f32_e32 v218, v218, v56
	s_waitcnt lgkmcnt(1)
	v_mfma_f32_32x32x16_bf16 v[32:47], v[158:161], v[234:237], v[32:47]
	v_add_f32_e32 v218, v218, v57
	v_add_f32_e32 v219, v219, v58
	v_add_f32_e32 v219, v219, v59
	v_add_f32_e32 v220, v220, v60
	s_waitcnt lgkmcnt(0)
	v_mfma_f32_32x32x16_bf16 v[16:31], v[162:165], v[234:237], v[16:31]
	v_add_f32_e32 v220, v220, v61
	v_add_f32_e32 v221, v221, v62
	v_add_f32_e32 v221, v221, v63
	v_add_f32_e32 v218, v218, v219
	v_add_f32_e32 v220, v220, v221
	v_add_f32_e32 v218, v218, v220
	v_add_f32_e32 v148, v148, v218
	s_andn2_b64 vcc, exec, s[0:1]
	s_cbranch_vccnz .LBB0_1170
	ds_write_b128 v134, v[80:83]
	s_and_saveexec_b64 s[0:1], s[4:5]
	s_cbranch_execz .LBB0_1169
	v_add_u32_e32 v67, v147, v135
	ds_write_b128 v67, v[84:87] offset:128
	s_branch .LBB0_1169
